# index PASS2: ballot idiom v_cndmask(0,1,mask)+v_cmp_ne replaced by s_and_b64 mask, exec (6 sites)
# speedup vs baseline: 1.0074x; 1.0027x over previous
; DI void phase_index(const Params& p, unsigned char* lds) {
;     ...
;                 } else {
;                     const int k20 = (int)(uk >> kshv[qq]);
;                     const u64 bg = __ballot(valid && k20 > tauv[qq]);
;                     const u64 be = __ballot(valid && k20 == tauv[qq]);
;                     Gm[qq] |= (bg & 0xffffffffull) << (32 * kb); Gm[2 + qq] |= (bg >> 32) << (32 * kb);
;                     Em[qq] |= (be & 0xffffffffull) << (32 * kb); Em[2 + qq] |= (be >> 32) << (32 * kb);
;                 }
.LBB0_3526:
	s_andn2_b64 vcc, exec, s[28:29]
	s_cbranch_vccnz .LBB0_3528
	v_permlane32_swap_b32_e32 v18, v20
	v_permlane32_swap_b32_e32 v19, v21
	v_pk_add_f32 v[18:19], v[18:19], v[20:21]
	v_or_b32_e32 v26, 32, v164
	v_pk_add_f32 v[18:19], v[18:19], 0 op_sel_hi:[1,0]
	v_cmp_le_i32_e32 vcc, v26, v95
	v_ashrrev_i32_e32 v21, 31, v18
	v_ashrrev_i32_e32 v20, 31, v19
	v_or_b32_e32 v21, 0x80000000, v21
	v_or_b32_e32 v20, 0x80000000, v20
	v_xor_b32_e32 v18, v21, v18
	v_xor_b32_e32 v19, v20, v19
	v_lshrrev_b32_e32 v18, v106, v18
	v_add_u32_e32 v26, 31, v164
	v_lshrrev_b32_e32 v19, v83, v19
	v_cmp_gt_i32_e64 s[28:29], v18, v100
	v_cmp_eq_u32_e64 s[30:31], v18, v100
	v_cmp_le_i32_e64 s[26:27], v26, v95
	s_and_b64 s[28:29], vcc, s[28:29]
	s_and_b64 s[30:31], vcc, s[30:31]
	v_cmp_gt_i32_e32 vcc, v19, v1
	s_and_b64 s[58:59], s[28:29], exec
	v_cmp_eq_u32_e64 s[28:29], v19, v1
	s_and_b64 s[68:69], s[30:31], exec
	s_and_b64 s[30:31], s[26:27], vcc
	s_and_b64 s[26:27], s[26:27], s[28:29]
	s_and_b64 s[30:31], s[30:31], exec
	s_and_b64 s[26:27], s[26:27], exec

; DI void phase_index(const Params& p, unsigned char* lds) {
;     ...
;                 } else {
;                     const int k20 = (int)(uk >> kshv[qq]);
;                     const u64 bg = __ballot(valid && k20 > tauv[qq]);
;                     const u64 be = __ballot(valid && k20 == tauv[qq]);
;                     Gm[qq] |= (bg & 0xffffffffull) << (32 * kb); Gm[2 + qq] |= (bg >> 32) << (32 * kb);
;                     Em[qq] |= (be & 0xffffffffull) << (32 * kb); Em[2 + qq] |= (be >> 32) << (32 * kb);
;                 }
.LBB0_3556:
	v_permlane32_swap_b32_e32 v114, v116
	v_permlane32_swap_b32_e32 v115, v117
	v_pk_add_f32 v[114:115], v[114:115], v[116:117]
	v_cmp_le_i32_e32 vcc, v164, v95
	v_pk_add_f32 v[114:115], v[114:115], 0 op_sel_hi:[1,0]
	v_cmp_le_i32_e64 s[26:27], v164, v101
	v_ashrrev_i32_e32 v117, 31, v114
	v_ashrrev_i32_e32 v116, 31, v115
	v_or_b32_e32 v117, 0x80000000, v117
	v_or_b32_e32 v116, 0x80000000, v116
	v_xor_b32_e32 v114, v117, v114
	v_xor_b32_e32 v115, v116, v115
	v_lshrrev_b32_e32 v114, v106, v114
	v_lshrrev_b32_e32 v115, v83, v115
	v_cmp_gt_i32_e64 s[28:29], v114, v100
	v_cmp_eq_u32_e64 s[30:31], v114, v100
	s_and_b64 s[28:29], vcc, s[28:29]
	s_and_b64 s[30:31], vcc, s[30:31]
	v_cmp_gt_i32_e32 vcc, v115, v1
	v_cndmask_b32_e64 v116, 0, 1, s[28:29]
	v_cmp_eq_u32_e64 s[28:29], v115, v1
	s_and_b64 s[56:57], s[30:31], exec
	s_and_b64 s[30:31], s[26:27], vcc
	s_and_b64 s[26:27], s[26:27], s[28:29]
	s_and_b64 s[50:51], s[30:31], exec
	v_cndmask_b32_e64 v114, 0, 1, s[26:27]
	v_cmp_ne_u32_e64 s[52:53], 0, v116
	v_cmp_ne_u32_e64 s[54:55], 0, v114
	s_add_i32 s1, s1, 1
	s_cmp_ge_i32 s1, s97
	s_cbranch_scc0 .LBB0_3523
	s_branch .LBB0_3524
